# grid barrier: non-leader workgroups wait on the cross-XCD arrival counter instead of the release generation word
# baseline (speedup 1.0000x reference)
.LBB0_86:
	v_readlane_b32 s4, v243, 5
	s_lshl_b32 s4, s4, 8
	v_readlane_b32 s6, v243, 3
	v_readlane_b32 s7, v243, 4
	s_add_u32 s4, s6, s4
	s_addc_u32 s5, s7, 0
	v_mov_b32_e32 v1, 0x1000
	v_mov_b32_e32 v3, 1
	global_atomic_add v3, v1, v3, s[4:5] offset:1024 sc0
	v_cvt_f32_u32_e32 v1, v2
	v_sub_u32_e32 v4, 0, v2
	v_rcp_iflag_f32_e32 v1, v1
	s_nop 0
	v_mul_f32_e32 v1, 0x4f7ffffe, v1
	v_cvt_u32_f32_e32 v1, v1
	v_mul_lo_u32 v4, v4, v1
	v_mul_hi_u32 v4, v1, v4
	v_add_u32_e32 v1, v1, v4
	s_waitcnt vmcnt(0)
	v_mul_hi_u32 v1, v3, v1
	v_mul_lo_u32 v4, v1, v2
	v_sub_u32_e32 v4, v3, v4
	v_add_u32_e32 v5, 1, v1
	v_cmp_ge_u32_e32 vcc, v4, v2
	v_add_u32_e32 v3, 1, v3
	s_nop 0
	v_cndmask_b32_e32 v1, v1, v5, vcc
	v_sub_u32_e32 v5, v4, v2
	v_cndmask_b32_e32 v4, v4, v5, vcc
	v_add_u32_e32 v5, 1, v1
	v_cmp_ge_u32_e32 vcc, v4, v2
	s_nop 1
	v_cndmask_b32_e32 v1, v1, v5, vcc
	v_mul_lo_u32 v4, v2, v1
	v_add_u32_e32 v2, v4, v2
	v_cmp_ne_u32_e32 vcc, v3, v2
	s_and_saveexec_b64 s[6:7], vcc
	s_xor_b64 s[6:7], exec, s[6:7]
	s_cbranch_execz .LBB0_100
	s_waitcnt lgkmcnt(0)
	v_mad_u32_u24 v16, v1, v0, v0
	buffer_inv sc1
	s_waitcnt vmcnt(0)
	v_mov_b32_e32 v0, 0xc3000
	global_load_dword v0, v0, s[92:93] offset:1024 sc1
	s_add_u32 s12, s92, 0xc3400
	s_addc_u32 s13, s93, 0
	s_waitcnt vmcnt(0)
	v_cmp_lt_u32_e32 vcc, v0, v16
	s_and_saveexec_b64 s[8:9], vcc
	s_cbranch_execz .LBB0_99
	s_add_u32 s10, s92, 0xc0200
	s_addc_u32 s11, s93, 0
	s_mov_b32 s26, 1
	s_mov_b64 s[16:17], 0
	v_mov_b32_e32 v0, 0
	s_branch .LBB0_90

.LBB0_92:
	global_load_dword v2, v0, s[12:13] sc1
	s_add_i32 s26, s26, 1
	s_mov_b64 s[22:23], -1
	s_waitcnt vmcnt(0)
	v_cmp_ge_u32_e32 vcc, v2, v16
	s_orn2_b64 s[20:21], vcc, exec
	s_branch .LBB0_89

.LBB0_391:
	v_readlane_b32 s4, v243, 5
	s_lshl_b32 s4, s4, 8
	v_readlane_b32 s6, v243, 3
	v_readlane_b32 s7, v243, 4
	s_add_u32 s4, s6, s4
	s_addc_u32 s5, s7, 0
	v_mov_b32_e32 v1, 0x1000
	v_mov_b32_e32 v3, 1
	global_atomic_add v3, v1, v3, s[4:5] offset:1024 sc0
	v_cvt_f32_u32_e32 v1, v2
	v_sub_u32_e32 v4, 0, v2
	v_rcp_iflag_f32_e32 v1, v1
	s_nop 0
	v_mul_f32_e32 v1, 0x4f7ffffe, v1
	v_cvt_u32_f32_e32 v1, v1
	v_mul_lo_u32 v4, v4, v1
	v_mul_hi_u32 v4, v1, v4
	v_add_u32_e32 v1, v1, v4
	s_waitcnt vmcnt(0)
	v_mul_hi_u32 v1, v3, v1
	v_mul_lo_u32 v4, v1, v2
	v_sub_u32_e32 v4, v3, v4
	v_add_u32_e32 v5, 1, v1
	v_cmp_ge_u32_e32 vcc, v4, v2
	v_add_u32_e32 v3, 1, v3
	s_nop 0
	v_cndmask_b32_e32 v1, v1, v5, vcc
	v_sub_u32_e32 v5, v4, v2
	v_cndmask_b32_e32 v4, v4, v5, vcc
	v_add_u32_e32 v5, 1, v1
	v_cmp_ge_u32_e32 vcc, v4, v2
	s_nop 1
	v_cndmask_b32_e32 v1, v1, v5, vcc
	v_mul_lo_u32 v4, v2, v1
	v_add_u32_e32 v2, v4, v2
	v_cmp_ne_u32_e32 vcc, v3, v2
	s_and_saveexec_b64 s[6:7], vcc
	s_xor_b64 s[6:7], exec, s[6:7]
	s_cbranch_execz .LBB0_405
	s_waitcnt lgkmcnt(0)
	v_mad_u32_u24 v16, v1, v0, v0
	buffer_inv sc1
	s_waitcnt vmcnt(0)
	v_mov_b32_e32 v0, 0xc3000
	global_load_dword v0, v0, s[92:93] offset:1024 sc1
	s_add_u32 s14, s92, 0xc3400
	s_addc_u32 s15, s93, 0
	s_waitcnt vmcnt(0)
	v_cmp_lt_u32_e32 vcc, v0, v16
	s_and_saveexec_b64 s[8:9], vcc
	s_cbranch_execz .LBB0_404
	s_add_u32 s10, s92, 0xc0200
	s_addc_u32 s11, s93, 0
	s_mov_b32 s26, 1
	s_mov_b64 s[16:17], 0
	v_mov_b32_e32 v0, 0
	s_branch .LBB0_395

.LBB0_397:
	global_load_dword v2, v0, s[14:15] sc1
	s_add_i32 s26, s26, 1
	s_mov_b64 s[22:23], -1
	s_waitcnt vmcnt(0)
	v_cmp_ge_u32_e32 vcc, v2, v16
	s_orn2_b64 s[20:21], vcc, exec
	s_branch .LBB0_394

.LBB0_606:
	v_readlane_b32 s2, v243, 5
	s_lshl_b32 s2, s2, 8
	v_readlane_b32 s4, v243, 3
	v_readlane_b32 s5, v243, 4
	s_add_u32 s2, s4, s2
	s_addc_u32 s3, s5, 0
	v_mov_b32_e32 v1, 0x1000
	v_mov_b32_e32 v3, 1
	global_atomic_add v3, v1, v3, s[2:3] offset:1024 sc0
	v_cvt_f32_u32_e32 v1, v2
	v_sub_u32_e32 v4, 0, v2
	v_rcp_iflag_f32_e32 v1, v1
	s_nop 0
	v_mul_f32_e32 v1, 0x4f7ffffe, v1
	v_cvt_u32_f32_e32 v1, v1
	v_mul_lo_u32 v4, v4, v1
	v_mul_hi_u32 v4, v1, v4
	v_add_u32_e32 v1, v1, v4
	s_waitcnt vmcnt(0)
	v_mul_hi_u32 v1, v3, v1
	v_mul_lo_u32 v4, v1, v2
	v_sub_u32_e32 v4, v3, v4
	v_add_u32_e32 v5, 1, v1
	v_cmp_ge_u32_e32 vcc, v4, v2
	v_add_u32_e32 v3, 1, v3
	s_nop 0
	v_cndmask_b32_e32 v1, v1, v5, vcc
	v_sub_u32_e32 v5, v4, v2
	v_cndmask_b32_e32 v4, v4, v5, vcc
	v_add_u32_e32 v5, 1, v1
	v_cmp_ge_u32_e32 vcc, v4, v2
	s_nop 1
	v_cndmask_b32_e32 v1, v1, v5, vcc
	v_mul_lo_u32 v4, v2, v1
	v_add_u32_e32 v2, v4, v2
	v_cmp_ne_u32_e32 vcc, v3, v2
	s_and_saveexec_b64 s[4:5], vcc
	s_xor_b64 s[4:5], exec, s[4:5]
	s_cbranch_execz .LBB0_620
	s_waitcnt lgkmcnt(0)
	v_mad_u32_u24 v16, v1, v0, v0
	buffer_inv sc1
	s_waitcnt vmcnt(0)
	v_mov_b32_e32 v0, 0xc3000
	global_load_dword v0, v0, s[92:93] offset:1024 sc1
	s_add_u32 s10, s92, 0xc3400
	s_addc_u32 s11, s93, 0
	s_waitcnt vmcnt(0)
	v_cmp_lt_u32_e32 vcc, v0, v16
	s_and_saveexec_b64 s[6:7], vcc
	s_cbranch_execz .LBB0_619
	s_add_u32 s8, s92, 0xc0200
	s_addc_u32 s9, s93, 0
	s_mov_b32 s24, 1
	s_mov_b64 s[14:15], 0
	v_mov_b32_e32 v0, 0
	s_branch .LBB0_610

.LBB0_612:
	global_load_dword v2, v0, s[10:11] sc1
	s_add_i32 s24, s24, 1
	s_mov_b64 s[20:21], -1
	s_waitcnt vmcnt(0)
	v_cmp_ge_u32_e32 vcc, v2, v16
	s_orn2_b64 s[18:19], vcc, exec
	s_branch .LBB0_609

.LBB0_1114:
	v_readlane_b32 s4, v243, 5
	s_lshl_b32 s4, s4, 8
	v_readlane_b32 s6, v243, 3
	v_readlane_b32 s7, v243, 4
	s_add_u32 s4, s6, s4
	s_addc_u32 s5, s7, 0
	v_mov_b32_e32 v1, 0x1000
	v_mov_b32_e32 v3, 1
	global_atomic_add v3, v1, v3, s[4:5] offset:1024 sc0
	v_cvt_f32_u32_e32 v1, v2
	v_sub_u32_e32 v4, 0, v2
	v_rcp_iflag_f32_e32 v1, v1
	s_nop 0
	v_mul_f32_e32 v1, 0x4f7ffffe, v1
	v_cvt_u32_f32_e32 v1, v1
	v_mul_lo_u32 v4, v4, v1
	v_mul_hi_u32 v4, v1, v4
	v_add_u32_e32 v1, v1, v4
	s_waitcnt vmcnt(0)
	v_mul_hi_u32 v1, v3, v1
	v_mul_lo_u32 v4, v1, v2
	v_sub_u32_e32 v4, v3, v4
	v_add_u32_e32 v5, 1, v1
	v_cmp_ge_u32_e32 vcc, v4, v2
	v_add_u32_e32 v3, 1, v3
	s_nop 0
	v_cndmask_b32_e32 v1, v1, v5, vcc
	v_sub_u32_e32 v5, v4, v2
	v_cndmask_b32_e32 v4, v4, v5, vcc
	v_add_u32_e32 v5, 1, v1
	v_cmp_ge_u32_e32 vcc, v4, v2
	s_nop 1
	v_cndmask_b32_e32 v1, v1, v5, vcc
	v_mul_lo_u32 v4, v2, v1
	v_add_u32_e32 v2, v4, v2
	v_cmp_ne_u32_e32 vcc, v3, v2
	s_and_saveexec_b64 s[6:7], vcc
	s_xor_b64 s[6:7], exec, s[6:7]
	s_cbranch_execz .LBB0_1128
	s_waitcnt lgkmcnt(0)
	v_mad_u32_u24 v16, v1, v0, v0
	buffer_inv sc1
	s_waitcnt vmcnt(0)
	v_mov_b32_e32 v0, 0xc3000
	global_load_dword v0, v0, s[92:93] offset:1024 sc1
	s_add_u32 s18, s92, 0xc3400
	s_addc_u32 s19, s93, 0
	s_waitcnt vmcnt(0)
	v_cmp_lt_u32_e32 vcc, v0, v16
	s_and_saveexec_b64 s[8:9], vcc
	s_cbranch_execz .LBB0_1127
	s_add_u32 s12, s92, 0xc0200
	s_addc_u32 s13, s93, 0
	s_mov_b32 s14, 1
	s_mov_b64 s[20:21], 0
	v_mov_b32_e32 v0, 0
	s_branch .LBB0_1118

.LBB0_1120:
	global_load_dword v2, v0, s[18:19] sc1
	s_add_i32 s14, s14, 1
	s_mov_b64 s[26:27], -1
	s_waitcnt vmcnt(0)
	v_cmp_ge_u32_e32 vcc, v2, v16
	s_orn2_b64 s[24:25], vcc, exec
	s_branch .LBB0_1117

.LBB0_1350:
	v_readlane_b32 s4, v243, 5
	s_lshl_b32 s4, s4, 8
	v_readlane_b32 s6, v243, 3
	v_readlane_b32 s7, v243, 4
	s_add_u32 s4, s6, s4
	s_addc_u32 s5, s7, 0
	v_mov_b32_e32 v1, 0x1000
	v_mov_b32_e32 v3, 1
	global_atomic_add v3, v1, v3, s[4:5] offset:1024 sc0
	v_cvt_f32_u32_e32 v1, v2
	v_sub_u32_e32 v4, 0, v2
	v_rcp_iflag_f32_e32 v1, v1
	s_nop 0
	v_mul_f32_e32 v1, 0x4f7ffffe, v1
	v_cvt_u32_f32_e32 v1, v1
	v_mul_lo_u32 v4, v4, v1
	v_mul_hi_u32 v4, v1, v4
	v_add_u32_e32 v1, v1, v4
	s_waitcnt vmcnt(0)
	v_mul_hi_u32 v1, v3, v1
	v_mul_lo_u32 v4, v1, v2
	v_sub_u32_e32 v4, v3, v4
	v_add_u32_e32 v5, 1, v1
	v_cmp_ge_u32_e32 vcc, v4, v2
	v_add_u32_e32 v3, 1, v3
	s_nop 0
	v_cndmask_b32_e32 v1, v1, v5, vcc
	v_sub_u32_e32 v5, v4, v2
	v_cndmask_b32_e32 v4, v4, v5, vcc
	v_add_u32_e32 v5, 1, v1
	v_cmp_ge_u32_e32 vcc, v4, v2
	s_nop 1
	v_cndmask_b32_e32 v1, v1, v5, vcc
	v_mul_lo_u32 v4, v2, v1
	v_add_u32_e32 v2, v4, v2
	v_cmp_ne_u32_e32 vcc, v3, v2
	s_and_saveexec_b64 s[6:7], vcc
	s_xor_b64 s[6:7], exec, s[6:7]
	s_cbranch_execz .LBB0_1364
	s_waitcnt lgkmcnt(0)
	v_mad_u32_u24 v16, v1, v0, v0
	buffer_inv sc1
	s_waitcnt vmcnt(0)
	v_mov_b32_e32 v0, 0xc3000
	global_load_dword v0, v0, s[92:93] offset:1024 sc1
	s_add_u32 s12, s92, 0xc3400
	s_addc_u32 s13, s93, 0
	s_waitcnt vmcnt(0)
	v_cmp_lt_u32_e32 vcc, v0, v16
	s_and_saveexec_b64 s[8:9], vcc
	s_cbranch_execz .LBB0_1363
	s_add_u32 s10, s92, 0xc0200
	s_addc_u32 s11, s93, 0
	s_mov_b32 s24, 1
	s_mov_b64 s[14:15], 0
	v_mov_b32_e32 v0, 0
	s_branch .LBB0_1354

.LBB0_1356:
	global_load_dword v2, v0, s[12:13] sc1
	s_add_i32 s24, s24, 1
	s_mov_b64 s[20:21], -1
	s_waitcnt vmcnt(0)
	v_cmp_ge_u32_e32 vcc, v2, v16
	s_orn2_b64 s[18:19], vcc, exec
	s_branch .LBB0_1353

.LBB0_2069:
	v_readlane_b32 s2, v243, 5
	s_lshl_b32 s2, s2, 8
	v_readlane_b32 s4, v243, 3
	v_readlane_b32 s5, v243, 4
	s_add_u32 s2, s4, s2
	s_addc_u32 s3, s5, 0
	v_mov_b32_e32 v1, 0x1000
	v_mov_b32_e32 v3, 1
	global_atomic_add v3, v1, v3, s[2:3] offset:1024 sc0
	v_cvt_f32_u32_e32 v1, v2
	v_sub_u32_e32 v4, 0, v2
	v_rcp_iflag_f32_e32 v1, v1
	s_nop 0
	v_mul_f32_e32 v1, 0x4f7ffffe, v1
	v_cvt_u32_f32_e32 v1, v1
	v_mul_lo_u32 v4, v4, v1
	v_mul_hi_u32 v4, v1, v4
	v_add_u32_e32 v1, v1, v4
	s_waitcnt vmcnt(0)
	v_mul_hi_u32 v1, v3, v1
	v_mul_lo_u32 v4, v1, v2
	v_sub_u32_e32 v4, v3, v4
	v_add_u32_e32 v5, 1, v1
	v_cmp_ge_u32_e32 vcc, v4, v2
	v_add_u32_e32 v3, 1, v3
	s_nop 0
	v_cndmask_b32_e32 v1, v1, v5, vcc
	v_sub_u32_e32 v5, v4, v2
	v_cndmask_b32_e32 v4, v4, v5, vcc
	v_add_u32_e32 v5, 1, v1
	v_cmp_ge_u32_e32 vcc, v4, v2
	s_nop 1
	v_cndmask_b32_e32 v1, v1, v5, vcc
	v_mul_lo_u32 v4, v2, v1
	v_add_u32_e32 v2, v4, v2
	v_cmp_ne_u32_e32 vcc, v3, v2
	s_and_saveexec_b64 s[4:5], vcc
	s_xor_b64 s[4:5], exec, s[4:5]
	s_cbranch_execz .LBB0_2083
	s_waitcnt lgkmcnt(0)
	v_mad_u32_u24 v16, v1, v0, v0
	buffer_inv sc1
	s_waitcnt vmcnt(0)
	v_mov_b32_e32 v0, 0xc3000
	global_load_dword v0, v0, s[92:93] offset:1024 sc1
	s_add_u32 s10, s92, 0xc3400
	s_addc_u32 s11, s93, 0
	s_waitcnt vmcnt(0)
	v_cmp_lt_u32_e32 vcc, v0, v16
	s_and_saveexec_b64 s[6:7], vcc
	s_cbranch_execz .LBB0_2082
	s_add_u32 s8, s92, 0xc0200
	s_addc_u32 s9, s93, 0
	s_mov_b32 s22, 1
	s_mov_b64 s[12:13], 0
	v_mov_b32_e32 v0, 0
	s_branch .LBB0_2073

.LBB0_2075:
	global_load_dword v2, v0, s[10:11] sc1
	s_add_i32 s22, s22, 1
	s_mov_b64 s[18:19], -1
	s_waitcnt vmcnt(0)
	v_cmp_ge_u32_e32 vcc, v2, v16
	s_orn2_b64 s[16:17], vcc, exec
	s_branch .LBB0_2072
